# SEL/WIN interior steps: rescale only when a row max exceeds the running max by more than 4 (log2 units), exact online softmax otherwise unchanged
# speedup vs baseline: 1.0163x; 1.0163x over previous
; __device__ __forceinline__ float red_max4(float x) {
;     auto a = __builtin_amdgcn_permlane16_swap(__float_as_uint(x), __float_as_uint(x), false, false); x = fmaxf(__uint_as_float(a[0]), __uint_as_float(a[1]));
;     auto b = __builtin_amdgcn_permlane32_swap(__float_as_uint(x), __float_as_uint(x), false, false); return fmaxf(__uint_as_float(b[0]), __uint_as_float(b[1]));
; }
; template <int CGM>
; __device__ __forceinline__ void step_int(const bf16x8 (&kf)[4][2], const bf16x8 (&q)[2][2], float farb, const bool (&selq)[2],
;                                          float (&m)[2], float (&l)[2], f32x4 (&o)[2][4], const unsigned char* Vs, int r, int fq) {
;     f32x4 s[2][4]; float mx[2] = {-1e30f, -1e30f};
; #pragma unroll
;     for (int cg_ = 0; cg_ < 2; ++cg_) if ((CGM >> cg_) & 1) { qk(s[cg_], kf, q[cg_], selq[cg_] ? farb - m[cg_] : -1e30f); mx[cg_] = red_max4(max16v(s[cg_])); }
;     if (__any(mx[0] > 0.f || mx[1] > 0.f)) {
; #pragma unroll
;         for (int cg_ = 0; cg_ < 2; ++cg_) if ((CGM >> cg_) & 1) {
;             const float d = fmaxf(mx[cg_], 0.f), sc = __builtin_amdgcn_exp2f(-d); m[cg_] += d; l[cg_] *= sc;
; #pragma unroll
;             for (int df = 0; df < 4; ++df) o[cg_][df] *= sc;
; #pragma unroll
;             for (int f = 0; f < 4; ++f) s[cg_][f] -= d;
;         }
;     }
.Lsel_c3:
	v_sub_f32_e32 v128, v18, v124
	v_sub_f32_e32 v144, v18, v125
	v_cndmask_b32_e64 v128, v148, v128, s[10:11]
	v_cndmask_b32_e64 v144, v148, v144, s[8:9]
	v_mov_b32_e32 v129, v128
	v_mov_b32_e32 v145, v144
	v_mov_b64_e32 v[130:131], v[128:129]
	v_mov_b64_e32 v[146:147], v[144:145]
	s_waitcnt lgkmcnt(7)
	v_mfma_f32_16x16x32_bf16 v[92:95], v[88:91], v[2:5], v[128:131]
	v_mfma_f32_16x16x32_bf16 v[108:111], v[88:91], v[10:13], v[144:147]
	s_waitcnt lgkmcnt(6)
	v_mfma_f32_16x16x32_bf16 v[96:99], v[80:83], v[2:5], v[128:131]
	v_mfma_f32_16x16x32_bf16 v[112:115], v[80:83], v[10:13], v[144:147]
	s_waitcnt lgkmcnt(5)
	v_mfma_f32_16x16x32_bf16 v[92:95], v[84:87], v[6:9], v[92:95]
	v_mfma_f32_16x16x32_bf16 v[108:111], v[84:87], v[14:17], v[108:111]
	s_waitcnt lgkmcnt(4)
	v_mfma_f32_16x16x32_bf16 v[96:99], v[76:79], v[6:9], v[96:99]
	v_mfma_f32_16x16x32_bf16 v[112:115], v[76:79], v[14:17], v[112:115]
	s_waitcnt lgkmcnt(3)
	v_mfma_f32_16x16x32_bf16 v[100:103], v[72:75], v[2:5], v[128:131]
	v_mfma_f32_16x16x32_bf16 v[116:119], v[72:75], v[10:13], v[144:147]
	s_waitcnt lgkmcnt(2)
	v_mfma_f32_16x16x32_bf16 v[104:107], v[60:63], v[2:5], v[128:131]
	v_mfma_f32_16x16x32_bf16 v[120:123], v[60:63], v[10:13], v[144:147]
	s_waitcnt lgkmcnt(1)
	v_mfma_f32_16x16x32_bf16 v[100:103], v[68:71], v[6:9], v[100:103]
	v_mfma_f32_16x16x32_bf16 v[116:119], v[68:71], v[14:17], v[116:119]
	s_waitcnt lgkmcnt(0)
	v_mfma_f32_16x16x32_bf16 v[104:107], v[64:67], v[6:9], v[104:107]
	v_mfma_f32_16x16x32_bf16 v[120:123], v[64:67], v[14:17], v[120:123]
	ds_read_b128 v[88:91], v143 offset:8192
	ds_read_b128 v[80:83], v143 offset:8704
	ds_read_b128 v[72:75], v143 offset:12288
	ds_read_b128 v[60:63], v143 offset:12800
	v_max3_f32 v128, v92, v93, v94
	v_max3_f32 v129, v95, v96, v97
	v_max3_f32 v144, v108, v109, v110
	v_max3_f32 v145, v111, v112, v113
	v_max3_f32 v130, v98, v99, v100
	v_max3_f32 v131, v101, v102, v103
	v_max3_f32 v146, v114, v115, v116
	v_max3_f32 v147, v117, v118, v119
	v_max3_f32 v128, v128, v104, v105
	v_max3_f32 v129, v129, v106, v107
	v_max3_f32 v144, v144, v120, v121
	v_max3_f32 v145, v145, v122, v123
	v_max3_f32 v128, v128, v129, v130
	v_max3_f32 v144, v144, v145, v146
	v_max_f32_e32 v128, v128, v131
	v_max_f32_e32 v144, v144, v147
	v_mov_b32_e32 v129, v128
	v_mov_b32_e32 v145, v144
	ds_read_b128 v[84:87], v142 offset:8192
	ds_read_b128 v[76:79], v142 offset:8704
	v_permlane16_swap_b32_e32 v128, v129
	v_permlane16_swap_b32_e32 v144, v145
	v_max_f32_e32 v128, v128, v129
	v_max_f32_e32 v144, v144, v145
	v_mov_b32_e32 v129, v128
	v_mov_b32_e32 v145, v144
	ds_read_b128 v[68:71], v142 offset:12288
	ds_read_b128 v[64:67], v142 offset:12800
	v_permlane32_swap_b32_e32 v128, v129
	v_permlane32_swap_b32_e32 v144, v145
	v_max_f32_e32 v128, v128, v129
	v_max_f32_e32 v144, v144, v145
	v_max_f32_e32 v129, v128, v144
	v_cmp_lt_f32_e32 vcc, 4.0, v129
	s_cbranch_vccz .Lsel_c3_exp
	v_max_f32_e32 v130, 0, v128
	v_max_f32_e32 v147, 0, v144
	v_exp_f32_e64 v128, -v130
	v_exp_f32_e64 v146, -v147
	v_add_f32_e32 v124, v124, v130
	v_add_f32_e32 v125, v125, v147
	v_sub_f32_e32 v92, v92, v130
	v_sub_f32_e32 v93, v93, v130
	v_sub_f32_e32 v94, v94, v130
	v_sub_f32_e32 v95, v95, v130
	v_sub_f32_e32 v96, v96, v130
	v_sub_f32_e32 v97, v97, v130
	v_sub_f32_e32 v98, v98, v130
	v_sub_f32_e32 v99, v99, v130
	v_sub_f32_e32 v100, v100, v130
	v_sub_f32_e32 v101, v101, v130
	v_sub_f32_e32 v102, v102, v130
	v_sub_f32_e32 v103, v103, v130
	v_sub_f32_e32 v104, v104, v130
	v_sub_f32_e32 v105, v105, v130
	v_sub_f32_e32 v106, v106, v130
	v_sub_f32_e32 v107, v107, v130
	v_sub_f32_e32 v108, v108, v147
	v_sub_f32_e32 v109, v109, v147
	v_sub_f32_e32 v110, v110, v147
	v_sub_f32_e32 v111, v111, v147
	v_sub_f32_e32 v112, v112, v147
	v_sub_f32_e32 v113, v113, v147
	v_sub_f32_e32 v114, v114, v147
	v_sub_f32_e32 v115, v115, v147
	v_sub_f32_e32 v116, v116, v147
	v_sub_f32_e32 v117, v117, v147
	v_sub_f32_e32 v118, v118, v147
	v_sub_f32_e32 v119, v119, v147
	v_sub_f32_e32 v120, v120, v147
	v_sub_f32_e32 v121, v121, v147
	v_sub_f32_e32 v122, v122, v147
	v_sub_f32_e32 v123, v123, v147
	v_mul_f32_e32 v127, v127, v128
	v_pk_mul_f32 v[56:57], v[56:57], v[128:129] op_sel_hi:[1,0]
	v_pk_mul_f32 v[58:59], v[58:59], v[128:129] op_sel_hi:[1,0]
	v_pk_mul_f32 v[52:53], v[52:53], v[128:129] op_sel_hi:[1,0]
	v_pk_mul_f32 v[54:55], v[54:55], v[128:129] op_sel_hi:[1,0]
	v_pk_mul_f32 v[48:49], v[48:49], v[128:129] op_sel_hi:[1,0]
	v_pk_mul_f32 v[50:51], v[50:51], v[128:129] op_sel_hi:[1,0]
	v_pk_mul_f32 v[44:45], v[44:45], v[128:129] op_sel_hi:[1,0]
	v_pk_mul_f32 v[46:47], v[46:47], v[128:129] op_sel_hi:[1,0]
	v_mul_f32_e32 v126, v126, v146
	v_pk_mul_f32 v[40:41], v[40:41], v[146:147] op_sel_hi:[1,0]
	v_pk_mul_f32 v[42:43], v[42:43], v[146:147] op_sel_hi:[1,0]
	v_pk_mul_f32 v[28:29], v[28:29], v[146:147] op_sel_hi:[1,0]
	v_pk_mul_f32 v[30:31], v[30:31], v[146:147] op_sel_hi:[1,0]
	v_pk_mul_f32 v[24:25], v[24:25], v[146:147] op_sel_hi:[1,0]
	v_pk_mul_f32 v[26:27], v[26:27], v[146:147] op_sel_hi:[1,0]
	v_pk_mul_f32 v[20:21], v[20:21], v[146:147] op_sel_hi:[1,0]
	v_pk_mul_f32 v[22:23], v[22:23], v[146:147] op_sel_hi:[1,0]

; __device__ __forceinline__ float red_max4(float x) {
;     auto a = __builtin_amdgcn_permlane16_swap(__float_as_uint(x), __float_as_uint(x), false, false); x = fmaxf(__uint_as_float(a[0]), __uint_as_float(a[1]));
;     auto b = __builtin_amdgcn_permlane32_swap(__float_as_uint(x), __float_as_uint(x), false, false); return fmaxf(__uint_as_float(b[0]), __uint_as_float(b[1]));
; }
; template <int CGM>
; __device__ __forceinline__ void step_int(const bf16x8 (&kf)[4][2], const bf16x8 (&q)[2][2], float farb, const bool (&selq)[2],
;                                          float (&m)[2], float (&l)[2], f32x4 (&o)[2][4], const unsigned char* Vs, int r, int fq) {
;     f32x4 s[2][4]; float mx[2] = {-1e30f, -1e30f};
; #pragma unroll
;     for (int cg_ = 0; cg_ < 2; ++cg_) if ((CGM >> cg_) & 1) { qk(s[cg_], kf, q[cg_], selq[cg_] ? farb - m[cg_] : -1e30f); mx[cg_] = red_max4(max16v(s[cg_])); }
;     if (__any(mx[0] > 0.f || mx[1] > 0.f)) {
; #pragma unroll
;         for (int cg_ = 0; cg_ < 2; ++cg_) if ((CGM >> cg_) & 1) {
;             const float d = fmaxf(mx[cg_], 0.f), sc = __builtin_amdgcn_exp2f(-d); m[cg_] += d; l[cg_] *= sc;
; #pragma unroll
;             for (int df = 0; df < 4; ++df) o[cg_][df] *= sc;
; #pragma unroll
;             for (int f = 0; f < 4; ++f) s[cg_][f] -= d;
;         }
;     }
.Lsel_c1:
	v_sub_f32_e32 v128, v18, v124
	v_cndmask_b32_e64 v128, v148, v128, s[10:11]
	v_mov_b32_e32 v129, v128
	v_mov_b64_e32 v[130:131], v[128:129]
	s_nop 0
	s_waitcnt lgkmcnt(7)
	v_mfma_f32_16x16x32_bf16 v[92:95], v[88:91], v[2:5], v[128:131]
	s_waitcnt lgkmcnt(6)
	v_mfma_f32_16x16x32_bf16 v[96:99], v[80:83], v[2:5], v[128:131]
	s_waitcnt lgkmcnt(5)
	v_mfma_f32_16x16x32_bf16 v[92:95], v[84:87], v[6:9], v[92:95]
	s_waitcnt lgkmcnt(4)
	v_mfma_f32_16x16x32_bf16 v[96:99], v[76:79], v[6:9], v[96:99]
	s_waitcnt lgkmcnt(3)
	v_mfma_f32_16x16x32_bf16 v[100:103], v[72:75], v[2:5], v[128:131]
	s_waitcnt lgkmcnt(2)
	v_mfma_f32_16x16x32_bf16 v[104:107], v[60:63], v[2:5], v[128:131]
	s_waitcnt lgkmcnt(1)
	v_mfma_f32_16x16x32_bf16 v[100:103], v[68:71], v[6:9], v[100:103]
	s_waitcnt lgkmcnt(0)
	v_mfma_f32_16x16x32_bf16 v[104:107], v[64:67], v[6:9], v[104:107]
	ds_read_b128 v[88:91], v143 offset:8192
	ds_read_b128 v[80:83], v143 offset:8704
	ds_read_b128 v[72:75], v143 offset:12288
	ds_read_b128 v[60:63], v143 offset:12800
	v_max3_f32 v128, v92, v93, v94
	v_max3_f32 v129, v95, v96, v97
	v_max3_f32 v130, v98, v99, v100
	v_max3_f32 v131, v101, v102, v103
	v_max3_f32 v128, v128, v104, v105
	v_max3_f32 v129, v129, v106, v107
	v_max3_f32 v128, v128, v129, v130
	v_max_f32_e32 v128, v128, v131
	v_mov_b32_e32 v129, v128
	ds_read_b128 v[84:87], v142 offset:8192
	ds_read_b128 v[76:79], v142 offset:8704
	v_permlane16_swap_b32_e32 v128, v129
	v_max_f32_e32 v128, v128, v129
	v_mov_b32_e32 v129, v128
	ds_read_b128 v[68:71], v142 offset:12288
	ds_read_b128 v[64:67], v142 offset:12800
	v_permlane32_swap_b32_e32 v128, v129
	v_max_f32_e32 v128, v128, v129
	v_cmp_lt_f32_e32 vcc, 4.0, v128
	s_cbranch_vccz .Lsel_c1_exp
	v_max_f32_e32 v130, 0, v128
	v_exp_f32_e64 v128, -v130
	v_add_f32_e32 v124, v124, v130
	v_sub_f32_e32 v92, v92, v130
	v_sub_f32_e32 v93, v93, v130
	v_sub_f32_e32 v94, v94, v130
	v_sub_f32_e32 v95, v95, v130
	v_sub_f32_e32 v96, v96, v130
	v_sub_f32_e32 v97, v97, v130
	v_sub_f32_e32 v98, v98, v130
	v_sub_f32_e32 v99, v99, v130
	v_sub_f32_e32 v100, v100, v130
	v_sub_f32_e32 v101, v101, v130
	v_sub_f32_e32 v102, v102, v130
	v_sub_f32_e32 v103, v103, v130
	v_sub_f32_e32 v104, v104, v130
	v_sub_f32_e32 v105, v105, v130
	v_sub_f32_e32 v106, v106, v130
	v_sub_f32_e32 v107, v107, v130
	v_mul_f32_e32 v127, v127, v128
	v_pk_mul_f32 v[56:57], v[56:57], v[128:129] op_sel_hi:[1,0]
	v_pk_mul_f32 v[58:59], v[58:59], v[128:129] op_sel_hi:[1,0]
	v_pk_mul_f32 v[52:53], v[52:53], v[128:129] op_sel_hi:[1,0]
	v_pk_mul_f32 v[54:55], v[54:55], v[128:129] op_sel_hi:[1,0]
	v_pk_mul_f32 v[48:49], v[48:49], v[128:129] op_sel_hi:[1,0]
	v_pk_mul_f32 v[50:51], v[50:51], v[128:129] op_sel_hi:[1,0]
	v_pk_mul_f32 v[44:45], v[44:45], v[128:129] op_sel_hi:[1,0]
	v_pk_mul_f32 v[46:47], v[46:47], v[128:129] op_sel_hi:[1,0]

; __device__ __forceinline__ float red_max4(float x) {
;     auto a = __builtin_amdgcn_permlane16_swap(__float_as_uint(x), __float_as_uint(x), false, false); x = fmaxf(__uint_as_float(a[0]), __uint_as_float(a[1]));
;     auto b = __builtin_amdgcn_permlane32_swap(__float_as_uint(x), __float_as_uint(x), false, false); return fmaxf(__uint_as_float(b[0]), __uint_as_float(b[1]));
; }
; template <int CGM>
; __device__ __forceinline__ void step_int(const bf16x8 (&kf)[4][2], const bf16x8 (&q)[2][2], float farb, const bool (&selq)[2],
;                                          float (&m)[2], float (&l)[2], f32x4 (&o)[2][4], const unsigned char* Vs, int r, int fq) {
;     f32x4 s[2][4]; float mx[2] = {-1e30f, -1e30f};
; #pragma unroll
;     for (int cg_ = 0; cg_ < 2; ++cg_) if ((CGM >> cg_) & 1) { qk(s[cg_], kf, q[cg_], selq[cg_] ? farb - m[cg_] : -1e30f); mx[cg_] = red_max4(max16v(s[cg_])); }
;     if (__any(mx[0] > 0.f || mx[1] > 0.f)) {
; #pragma unroll
;         for (int cg_ = 0; cg_ < 2; ++cg_) if ((CGM >> cg_) & 1) {
;             const float d = fmaxf(mx[cg_], 0.f), sc = __builtin_amdgcn_exp2f(-d); m[cg_] += d; l[cg_] *= sc;
; #pragma unroll
;             for (int df = 0; df < 4; ++df) o[cg_][df] *= sc;
; #pragma unroll
;             for (int f = 0; f < 4; ++f) s[cg_][f] -= d;
;         }
;     }
.Lsel_c2:
	v_sub_f32_e32 v144, v18, v125
	v_cndmask_b32_e64 v144, v148, v144, s[8:9]
	v_mov_b32_e32 v145, v144
	v_mov_b64_e32 v[146:147], v[144:145]
	s_nop 0
	s_waitcnt lgkmcnt(7)
	v_mfma_f32_16x16x32_bf16 v[108:111], v[88:91], v[10:13], v[144:147]
	s_waitcnt lgkmcnt(6)
	v_mfma_f32_16x16x32_bf16 v[112:115], v[80:83], v[10:13], v[144:147]
	s_waitcnt lgkmcnt(5)
	v_mfma_f32_16x16x32_bf16 v[108:111], v[84:87], v[14:17], v[108:111]
	s_waitcnt lgkmcnt(4)
	v_mfma_f32_16x16x32_bf16 v[112:115], v[76:79], v[14:17], v[112:115]
	s_waitcnt lgkmcnt(3)
	v_mfma_f32_16x16x32_bf16 v[116:119], v[72:75], v[10:13], v[144:147]
	s_waitcnt lgkmcnt(2)
	v_mfma_f32_16x16x32_bf16 v[120:123], v[60:63], v[10:13], v[144:147]
	s_waitcnt lgkmcnt(1)
	v_mfma_f32_16x16x32_bf16 v[116:119], v[68:71], v[14:17], v[116:119]
	s_waitcnt lgkmcnt(0)
	v_mfma_f32_16x16x32_bf16 v[120:123], v[64:67], v[14:17], v[120:123]
	ds_read_b128 v[88:91], v143 offset:8192
	ds_read_b128 v[80:83], v143 offset:8704
	ds_read_b128 v[72:75], v143 offset:12288
	ds_read_b128 v[60:63], v143 offset:12800
	v_max3_f32 v144, v108, v109, v110
	v_max3_f32 v145, v111, v112, v113
	v_max3_f32 v146, v114, v115, v116
	v_max3_f32 v147, v117, v118, v119
	v_max3_f32 v144, v144, v120, v121
	v_max3_f32 v145, v145, v122, v123
	v_max3_f32 v144, v144, v145, v146
	v_max_f32_e32 v144, v144, v147
	v_mov_b32_e32 v145, v144
	ds_read_b128 v[84:87], v142 offset:8192
	ds_read_b128 v[76:79], v142 offset:8704
	v_permlane16_swap_b32_e32 v144, v145
	v_max_f32_e32 v144, v144, v145
	v_mov_b32_e32 v145, v144
	ds_read_b128 v[68:71], v142 offset:12288
	ds_read_b128 v[64:67], v142 offset:12800
	v_permlane32_swap_b32_e32 v144, v145
	v_max_f32_e32 v144, v144, v145
	v_cmp_lt_f32_e32 vcc, 4.0, v144
	s_cbranch_vccz .Lsel_c2_exp
	v_max_f32_e32 v147, 0, v144
	v_exp_f32_e64 v146, -v147
	v_add_f32_e32 v125, v125, v147
	v_sub_f32_e32 v108, v108, v147
	v_sub_f32_e32 v109, v109, v147
	v_sub_f32_e32 v110, v110, v147
	v_sub_f32_e32 v111, v111, v147
	v_sub_f32_e32 v112, v112, v147
	v_sub_f32_e32 v113, v113, v147
	v_sub_f32_e32 v114, v114, v147
	v_sub_f32_e32 v115, v115, v147
	v_sub_f32_e32 v116, v116, v147
	v_sub_f32_e32 v117, v117, v147
	v_sub_f32_e32 v118, v118, v147
	v_sub_f32_e32 v119, v119, v147
	v_sub_f32_e32 v120, v120, v147
	v_sub_f32_e32 v121, v121, v147
	v_sub_f32_e32 v122, v122, v147
	v_sub_f32_e32 v123, v123, v147
	v_mul_f32_e32 v126, v126, v146
	v_pk_mul_f32 v[40:41], v[40:41], v[146:147] op_sel_hi:[1,0]
	v_pk_mul_f32 v[42:43], v[42:43], v[146:147] op_sel_hi:[1,0]
	v_pk_mul_f32 v[28:29], v[28:29], v[146:147] op_sel_hi:[1,0]
	v_pk_mul_f32 v[30:31], v[30:31], v[146:147] op_sel_hi:[1,0]
	v_pk_mul_f32 v[24:25], v[24:25], v[146:147] op_sel_hi:[1,0]
	v_pk_mul_f32 v[26:27], v[26:27], v[146:147] op_sel_hi:[1,0]
	v_pk_mul_f32 v[20:21], v[20:21], v[146:147] op_sel_hi:[1,0]
	v_pk_mul_f32 v[22:23], v[22:23], v[146:147] op_sel_hi:[1,0]

; __device__ __forceinline__ float red_max4(float x) {
;     auto a = __builtin_amdgcn_permlane16_swap(__float_as_uint(x), __float_as_uint(x), false, false); x = fmaxf(__uint_as_float(a[0]), __uint_as_float(a[1]));
;     auto b = __builtin_amdgcn_permlane32_swap(__float_as_uint(x), __float_as_uint(x), false, false); return fmaxf(__uint_as_float(b[0]), __uint_as_float(b[1]));
; }
; template <int CGM>
; __device__ __forceinline__ void step_int(const bf16x8 (&kf)[4][2], const bf16x8 (&q)[2][2], float farb, const bool (&selq)[2],
;                                          float (&m)[2], float (&l)[2], f32x4 (&o)[2][4], const unsigned char* Vs, int r, int fq) {
;     f32x4 s[2][4]; float mx[2] = {-1e30f, -1e30f};
; #pragma unroll
;     for (int cg_ = 0; cg_ < 2; ++cg_) if ((CGM >> cg_) & 1) { qk(s[cg_], kf, q[cg_], selq[cg_] ? farb - m[cg_] : -1e30f); mx[cg_] = red_max4(max16v(s[cg_])); }
;     if (__any(mx[0] > 0.f || mx[1] > 0.f)) {
; #pragma unroll
;         for (int cg_ = 0; cg_ < 2; ++cg_) if ((CGM >> cg_) & 1) {
;             const float d = fmaxf(mx[cg_], 0.f), sc = __builtin_amdgcn_exp2f(-d); m[cg_] += d; l[cg_] *= sc;
; #pragma unroll
;             for (int df = 0; df < 4; ++df) o[cg_][df] *= sc;
; #pragma unroll
;             for (int f = 0; f < 4; ++f) s[cg_][f] -= d;
;         }
;     }
.Lwin_int:
	v_sub_f32_e32 v188, v18, v156
	v_sub_f32_e32 v192, v18, v157
	v_mov_b32_e32 v189, v188
	v_mov_b32_e32 v193, v192
	v_mov_b64_e32 v[190:191], v[188:189]
	v_mov_b64_e32 v[194:195], v[192:193]
	s_waitcnt lgkmcnt(7)
	v_mfma_f32_16x16x32_bf16 v[116:119], v[80:83], v[2:5], v[188:191]
	v_mfma_f32_16x16x32_bf16 v[136:139], v[80:83], v[10:13], v[192:195]
	s_waitcnt lgkmcnt(6)
	v_mfma_f32_16x16x32_bf16 v[120:123], v[72:75], v[2:5], v[188:191]
	v_mfma_f32_16x16x32_bf16 v[140:143], v[72:75], v[10:13], v[192:195]
	s_waitcnt lgkmcnt(5)
	v_mfma_f32_16x16x32_bf16 v[116:119], v[76:79], v[6:9], v[116:119]
	v_mfma_f32_16x16x32_bf16 v[136:139], v[76:79], v[14:17], v[136:139]
	s_waitcnt lgkmcnt(4)
	v_mfma_f32_16x16x32_bf16 v[120:123], v[68:71], v[6:9], v[120:123]
	v_mfma_f32_16x16x32_bf16 v[140:143], v[68:71], v[14:17], v[140:143]
	s_waitcnt lgkmcnt(3)
	v_mfma_f32_16x16x32_bf16 v[124:127], v[60:63], v[2:5], v[188:191]
	v_mfma_f32_16x16x32_bf16 v[144:147], v[60:63], v[10:13], v[192:195]
	s_waitcnt lgkmcnt(2)
	v_mfma_f32_16x16x32_bf16 v[132:135], v[56:59], v[2:5], v[188:191]
	v_mfma_f32_16x16x32_bf16 v[184:187], v[56:59], v[10:13], v[192:195]
	s_waitcnt lgkmcnt(1)
	v_mfma_f32_16x16x32_bf16 v[124:127], v[64:67], v[6:9], v[124:127]
	v_mfma_f32_16x16x32_bf16 v[144:147], v[64:67], v[14:17], v[144:147]
	s_waitcnt lgkmcnt(0)
	v_mfma_f32_16x16x32_bf16 v[132:135], v[52:55], v[6:9], v[132:135]
	v_mfma_f32_16x16x32_bf16 v[184:187], v[52:55], v[14:17], v[184:187]
	ds_read_b128 v[80:83], v149 offset:8192
	ds_read_b128 v[72:75], v149 offset:8704
	ds_read_b128 v[60:63], v149 offset:12288
	ds_read_b128 v[56:59], v149 offset:12800
	v_max3_f32 v188, v116, v117, v118
	v_max3_f32 v189, v119, v120, v121
	v_max3_f32 v192, v136, v137, v138
	v_max3_f32 v193, v139, v140, v141
	v_max3_f32 v190, v122, v123, v124
	v_max3_f32 v191, v125, v126, v127
	v_max3_f32 v194, v142, v143, v144
	v_max3_f32 v195, v145, v146, v147
	v_max3_f32 v188, v188, v132, v133
	v_max3_f32 v189, v189, v134, v135
	v_max3_f32 v192, v192, v184, v185
	v_max3_f32 v193, v193, v186, v187
	v_max3_f32 v188, v188, v189, v190
	v_max3_f32 v192, v192, v193, v194
	v_max_f32_e32 v188, v188, v191
	v_max_f32_e32 v192, v192, v195
	v_mov_b32_e32 v189, v188
	v_mov_b32_e32 v193, v192
	ds_read_b128 v[76:79], v182 offset:8192
	ds_read_b128 v[68:71], v182 offset:8704
	v_permlane16_swap_b32_e32 v188, v189
	v_permlane16_swap_b32_e32 v192, v193
	v_max_f32_e32 v188, v188, v189
	v_max_f32_e32 v192, v192, v193
	v_mov_b32_e32 v189, v188
	v_mov_b32_e32 v193, v192
	ds_read_b128 v[64:67], v182 offset:12288
	ds_read_b128 v[52:55], v182 offset:12800
	v_permlane32_swap_b32_e32 v188, v189
	v_permlane32_swap_b32_e32 v192, v193
	v_max_f32_e32 v188, v188, v189
	v_max_f32_e32 v192, v192, v193
	v_max_f32_e32 v189, v188, v192
	v_cmp_lt_f32_e32 vcc, 4.0, v189
	s_cbranch_vccz .Lwin_int_exp
	v_max_f32_e32 v190, 0, v188
	v_max_f32_e32 v195, 0, v192
	v_exp_f32_e64 v188, -v190
	v_exp_f32_e64 v194, -v195
	v_add_f32_e32 v156, v156, v190
	v_add_f32_e32 v157, v157, v195
	v_sub_f32_e32 v116, v116, v190
	v_sub_f32_e32 v117, v117, v190
	v_sub_f32_e32 v118, v118, v190
	v_sub_f32_e32 v119, v119, v190
	v_sub_f32_e32 v120, v120, v190
	v_sub_f32_e32 v121, v121, v190
	v_sub_f32_e32 v122, v122, v190
	v_sub_f32_e32 v123, v123, v190
	v_sub_f32_e32 v124, v124, v190
	v_sub_f32_e32 v125, v125, v190
	v_sub_f32_e32 v126, v126, v190
	v_sub_f32_e32 v127, v127, v190
	v_sub_f32_e32 v132, v132, v190
	v_sub_f32_e32 v133, v133, v190
	v_sub_f32_e32 v134, v134, v190
	v_sub_f32_e32 v135, v135, v190
	v_sub_f32_e32 v136, v136, v195
	v_sub_f32_e32 v137, v137, v195
	v_sub_f32_e32 v138, v138, v195
	v_sub_f32_e32 v139, v139, v195
	v_sub_f32_e32 v140, v140, v195
	v_sub_f32_e32 v141, v141, v195
	v_sub_f32_e32 v142, v142, v195
	v_sub_f32_e32 v143, v143, v195
	v_sub_f32_e32 v144, v144, v195
	v_sub_f32_e32 v145, v145, v195
	v_sub_f32_e32 v146, v146, v195
	v_sub_f32_e32 v147, v147, v195
	v_sub_f32_e32 v184, v184, v195
	v_sub_f32_e32 v185, v185, v195
	v_sub_f32_e32 v186, v186, v195
	v_sub_f32_e32 v187, v187, v195
	v_mul_f32_e32 v155, v155, v188
	v_pk_mul_f32 v[48:49], v[48:49], v[188:189] op_sel_hi:[1,0]
	v_pk_mul_f32 v[50:51], v[50:51], v[188:189] op_sel_hi:[1,0]
	v_pk_mul_f32 v[40:41], v[40:41], v[188:189] op_sel_hi:[1,0]
	v_pk_mul_f32 v[42:43], v[42:43], v[188:189] op_sel_hi:[1,0]
	v_pk_mul_f32 v[32:33], v[32:33], v[188:189] op_sel_hi:[1,0]
	v_pk_mul_f32 v[34:35], v[34:35], v[188:189] op_sel_hi:[1,0]
	v_pk_mul_f32 v[24:25], v[24:25], v[188:189] op_sel_hi:[1,0]
	v_pk_mul_f32 v[26:27], v[26:27], v[188:189] op_sel_hi:[1,0]
	v_mul_f32_e32 v154, v154, v194
	v_pk_mul_f32 v[44:45], v[44:45], v[194:195] op_sel_hi:[1,0]
	v_pk_mul_f32 v[46:47], v[46:47], v[194:195] op_sel_hi:[1,0]
	v_pk_mul_f32 v[36:37], v[36:37], v[194:195] op_sel_hi:[1,0]
	v_pk_mul_f32 v[38:39], v[38:39], v[194:195] op_sel_hi:[1,0]
	v_pk_mul_f32 v[28:29], v[28:29], v[194:195] op_sel_hi:[1,0]
	v_pk_mul_f32 v[30:31], v[30:31], v[194:195] op_sel_hi:[1,0]
	v_pk_mul_f32 v[20:21], v[20:21], v[194:195] op_sel_hi:[1,0]
	v_pk_mul_f32 v[22:23], v[22:23], v[194:195] op_sel_hi:[1,0]
